# retention S phase: K fragments 8-15 read via offset:256 from the addresses of fragments 0-7 (24 address VALU per tile removed from the MFMA chain)
# speedup vs baseline: 1.0044x; 1.0038x over previous
; #define LAS __attribute__((address_space(3)))
; __device__ __forceinline__ unsigned cvt_pk_bf16(float lo, float hi) { unsigned r; asm volatile("v_cvt_pk_bf16_f32 %0, %1, %2" : "=v"(r) : "v"(lo), "v"(hi)); return r; }
; #define RT_KRD(dst, s0) do { _Pragma("unroll") for (int j_ = 0; j_ < 2; ++j_) dst[j_] = *(const LAS bf16x8*)(kb + ((((2 * ((s0) + j_)) | hh) ^ x15) << 4)); } while (0)
; __device__ __forceinline__ void p2_ret(const Frame& F, ArgsP a, int layer) {
;     ...
;                 { const LAS unsigned char* kb = lds + RT_K0 + bf * 32768 + (32 * wc + kap) * 512;
;     ...
;                   bf16x8 ka[2], kd[2], kc[2];
;                   RT_KRD(ka, 0); RT_KRD(kd, 2); __builtin_amdgcn_sched_barrier(0);
;                   RT_KRD(kc, 4); RT_KMM(ka, 0); if (pre) { RT_DMA_K(kt + 1, bf ^ 1, 0); RT_DMA_V(kt + 1, bf ^ 1, 0); } __builtin_amdgcn_sched_barrier(0);
;                   RT_KRD(ka, 6); RT_KMM(kd, 2); __builtin_amdgcn_sched_barrier(0);
;                   RT_KRD(kd, 8); RT_KMM(kc, 4); if (pre) { RT_DMA_K(kt + 1, bf ^ 1, 1); RT_DMA_V(kt + 1, bf ^ 1, 1); } __builtin_amdgcn_sched_barrier(0);
;                   RT_KRD(kc, 10); RT_KMM(ka, 6); __builtin_amdgcn_sched_barrier(0);
;                   RT_KRD(ka, 12); RT_KMM(kd, 8); if (pre) { RT_DMA_K(kt + 1, bf ^ 1, 2); RT_DMA_V(kt + 1, bf ^ 1, 2); } __builtin_amdgcn_sched_barrier(0);
;                   RT_KRD(kd, 14); RT_KMM(kc, 10); __builtin_amdgcn_sched_barrier(0);
;                   RT_KMM(ka, 12); if (pre) { RT_DMA_K(kt + 1, bf ^ 1, 3); RT_DMA_V(kt + 1, bf ^ 1, 3); } __builtin_amdgcn_sched_barrier(0);
;                   RT_KMM(kd, 14); __builtin_amdgcn_sched_barrier(0);
;     ...
;                 }
;                 { const bool diag = kt >= 2 * qi;
;                   unsigned pk[8];
;                   if (!diag) { const float tf = __builtin_amdgcn_exp2f((float)(128 * (qi - (kt >> 1))) * lg2);
; #pragma unroll
;                       for (int i = 0; i < 8; ++i) pk[i] = cvt_pk_bf16(st[2 * i] * tf, st[2 * i + 1] * tf);
;                   } else { const int lim = wr * 32 + l31 + (2 * qi - kt) * 64 - 32 * wc - 8 * hh;
; #pragma unroll
;                       for (int i = 0; i < 8; ++i) { const int r0 = 2 * i, r1 = 2 * i + 1, o0 = 16 * (r0 >> 3) + (r0 & 7), o1 = 16 * (r1 >> 3) + (r1 & 7);
;                           pk[i] = cvt_pk_bf16((o0 <= lim) ? st[r0] : 0.f, (o1 <= lim) ? st[r1] : 0.f); } }
.LBB0_383:
	v_mov_b32_e32 v0, v207
	s_and_b32 s6, s31, 0x8000
	v_lshlrev_b32_e32 v99, 1, v0
	v_lshrrev_b32_e32 v100, 1, v0
	v_and_b32_e32 v98, 19, v0
	v_and_b32_e32 v99, 8, v99
	v_and_b32_e32 v100, 4, v100
	v_or3_b32 v115, v99, v98, v100
	v_ashrrev_i32_e32 v116, 5, v0
	s_add_i32 s4, s6, 0
	v_or_b32_e32 v98, s80, v115
	v_lshl_add_u32 v227, v98, 9, s4
	v_bitop3_b32 v228, v115, v116, 15 bitop3:0x6c
	v_or_b32_e32 v229, 2, v116
	v_bitop3_b32 v229, v115, v229, 15 bitop3:0x6c
	v_lshl_add_u32 v228, v228, 4, v227
	v_lshl_add_u32 v229, v229, 4, v227
	ds_read_b128 v[98:101], v228
	ds_read_b128 v[190:193], v229
	v_or_b32_e32 v230, 4, v116
	v_bitop3_b32 v230, v115, v230, 15 bitop3:0x6c
	v_or_b32_e32 v231, 6, v116
	v_lshl_add_u32 v230, v230, 4, v227
	v_bitop3_b32 v231, v115, v231, 15 bitop3:0x6c
	v_lshl_add_u32 v231, v231, 4, v227
	ds_read_b128 v[194:197], v230
	ds_read_b128 v[198:201], v231
	v_and_b32_e32 v117, 31, v0
	v_or_b32_e32 v250, 8, v116
	s_xor_b32 s4, s6, 0x8000
	v_bitop3_b32 v250, v115, v250, 15 bitop3:0x6c
	v_or_b32_e32 v251, 10, v116
	s_add_i32 s5, s22, s4
	v_lshl_add_u32 v250, v250, 4, v227
	v_bitop3_b32 v251, v115, v251, 15 bitop3:0x6c
	v_lshl_add_u32 v251, v251, 4, v227
	ds_read_b128 v[202:205], v250
	ds_read_b128 v[212:215], v251
	s_add_i32 s7, s25, s30
	s_add_i32 m0, s33, s4
	s_add_i32 s12, s7, 0x80
	s_mov_b32 s46, s42
	s_mov_b32 s47, s43
	buffer_load_dwordx4 v225, s[44:47], s12 offen lds
	s_waitcnt lgkmcnt(5)
	v_mfma_f32_32x32x16_bf16 v[98:113], v[98:101], v[118:121], 0
	s_waitcnt lgkmcnt(4)
	v_mfma_f32_32x32x16_bf16 v[98:113], v[190:193], v[122:125], v[98:113]
	v_or_b32_e32 v252, 12, v116
	v_or_b32_e32 v253, 14, v116
	v_bitop3_b32 v252, v115, v252, 15 bitop3:0x6c
	v_bitop3_b32 v253, v115, v253, 15 bitop3:0x6c
	v_lshl_add_u32 v252, v252, 4, v227
	v_lshl_add_u32 v253, v253, 4, v227
	ds_read_b128 v[190:193], v252
	ds_read_b128 v[216:219], v253
	s_waitcnt lgkmcnt(5)
	v_mfma_f32_32x32x16_bf16 v[98:113], v[194:197], v[126:129], v[98:113]
	s_add_i32 s4, s4, 0
	s_waitcnt lgkmcnt(4)
	v_mfma_f32_32x32x16_bf16 v[98:113], v[198:201], v[130:133], v[98:113]
	s_add_i32 s12, s27, 0xfffe0000
	s_add_i32 s4, s4, 0x10000
	ds_read_b128 v[194:197], v228 offset:256
	ds_read_b128 v[198:201], v229 offset:256
	s_add_i32 m0, s4, s24
	s_add_i32 s12, s7, 0x100080
	buffer_load_dwordx4 v225, s[44:47], s12 offen lds
	s_waitcnt lgkmcnt(5)
	v_mfma_f32_32x32x16_bf16 v[98:113], v[202:205], v[134:137], v[98:113]
	s_waitcnt lgkmcnt(4)
	v_mfma_f32_32x32x16_bf16 v[98:113], v[212:215], v[138:141], v[98:113]
	ds_read_b128 v[202:205], v230 offset:256
	ds_read_b128 v[212:215], v231 offset:256
	s_waitcnt lgkmcnt(5)
	v_mfma_f32_32x32x16_bf16 v[98:113], v[190:193], v[142:145], v[98:113]
	s_add_i32 s12, s27, 0xffff0000
	s_waitcnt lgkmcnt(4)
	v_mfma_f32_32x32x16_bf16 v[98:113], v[216:219], v[146:149], v[98:113]
	ds_read_b128 v[190:193], v250 offset:256
	ds_read_b128 v[216:219], v251 offset:256
	s_add_i32 m0, s4, s26
	s_add_i32 s12, s7, 0x200080
	buffer_load_dwordx4 v225, s[44:47], s12 offen lds
	s_waitcnt lgkmcnt(5)
	v_mfma_f32_32x32x16_bf16 v[98:113], v[194:197], v[150:153], v[98:113]
	s_waitcnt lgkmcnt(4)
	v_mfma_f32_32x32x16_bf16 v[98:113], v[198:201], v[154:157], v[98:113]
	s_waitcnt lgkmcnt(3)
	v_mfma_f32_32x32x16_bf16 v[98:113], v[202:205], v[158:161], v[98:113]
	ds_read_b128 v[194:197], v252 offset:256
	ds_read_b128 v[198:201], v253 offset:256
	s_waitcnt lgkmcnt(4)
	v_mfma_f32_32x32x16_bf16 v[98:113], v[212:215], v[162:165], v[98:113]
	s_add_i32 s7, s7, 0x300080
	s_add_i32 m0, s4, s28
	s_waitcnt lgkmcnt(3)
	v_mfma_f32_32x32x16_bf16 v[98:113], v[190:193], v[166:169], v[98:113]
	buffer_load_dwordx4 v225, s[44:47], s7 offen lds
	s_waitcnt lgkmcnt(2)
	v_mfma_f32_32x32x16_bf16 v[98:113], v[216:219], v[170:173], v[98:113]
	s_waitcnt lgkmcnt(1)
	v_mfma_f32_32x32x16_bf16 v[98:113], v[194:197], v[174:177], v[98:113]
	s_waitcnt lgkmcnt(0)
	v_mfma_f32_32x32x16_bf16 v[98:113], v[198:201], v[178:181], v[98:113]
	v_lshlrev_b32_e32 v250, 3, v115
	v_and_b32_e32 v250, 0x70, v250
	s_add_i32 s13, s64, s6
	v_lshl_add_u32 v251, v115, 7, s13
	v_lshlrev_b32_e32 v252, 4, v116
	s_lshl_b32 s14, s80, 1
	v_xad_u32 v246, v250, v252, v251
	v_add_u32_e32 v253, 32, v252
	v_xad_u32 v247, v250, v253, v251
	v_xor_b32_e32 v246, s14, v246
	v_xor_b32_e32 v247, s14, v247
	v_xor_b32_e32 v248, 64, v246
	v_xor_b32_e32 v249, 64, v247
	ds_read_b128 v[234:237], v246
	ds_read_b128 v[238:241], v247
	s_cmp_ge_u32 s91, s29
	s_mov_b64 s[4:5], -1
	s_cbranch_scc0 .LBB0_385
	v_lshlrev_b32_e32 v190, 3, v116
	v_sub_u32_e32 v117, v117, v190
	v_add_u32_e32 v117, s97, v117
	v_cmp_lt_i32_e32 vcc, -1, v117
	s_mov_b64 s[4:5], 0
	s_nop 3
	v_cndmask_b32_e32 v190, 0, v98, vcc
	v_cmp_lt_i32_e32 vcc, 0, v117
	s_nop 1
	v_cndmask_b32_e32 v191, 0, v99, vcc
	v_cmp_lt_i32_e32 vcc, 1, v117
	v_cvt_pk_bf16_f32 v190, v190, v191
	s_nop 1
	v_cndmask_b32_e32 v191, 0, v100, vcc
	v_cmp_lt_i32_e32 vcc, 2, v117
	s_nop 1
	v_cndmask_b32_e32 v192, 0, v101, vcc
	v_cmp_lt_i32_e32 vcc, 3, v117
	v_cvt_pk_bf16_f32 v191, v191, v192
	s_nop 1
	v_cndmask_b32_e32 v192, 0, v102, vcc
	v_cmp_lt_i32_e32 vcc, 4, v117
	s_nop 1
	v_cndmask_b32_e32 v193, 0, v103, vcc
	v_cmp_lt_i32_e32 vcc, 5, v117
	v_cvt_pk_bf16_f32 v192, v192, v193
	s_nop 1
	v_cndmask_b32_e32 v193, 0, v104, vcc
	v_cmp_lt_i32_e32 vcc, 6, v117
	s_nop 1
	v_cndmask_b32_e32 v194, 0, v105, vcc
	v_cmp_lt_i32_e32 vcc, 15, v117
	v_cvt_pk_bf16_f32 v193, v193, v194
	s_nop 1
	v_cndmask_b32_e32 v194, 0, v106, vcc
	v_cmp_lt_i32_e32 vcc, 16, v117
	s_nop 1
	v_cndmask_b32_e32 v195, 0, v107, vcc
	v_cmp_lt_i32_e32 vcc, 17, v117
	v_cvt_pk_bf16_f32 v194, v194, v195
	s_nop 1
	v_cndmask_b32_e32 v195, 0, v108, vcc
	v_cmp_lt_i32_e32 vcc, 18, v117
	s_nop 1
	v_cndmask_b32_e32 v196, 0, v109, vcc
	v_cmp_lt_i32_e32 vcc, 19, v117
	v_cvt_pk_bf16_f32 v195, v195, v196
	s_nop 1
	v_cndmask_b32_e32 v196, 0, v110, vcc
	v_cmp_lt_i32_e32 vcc, 20, v117
	s_nop 1
	v_cndmask_b32_e32 v197, 0, v111, vcc
	v_cmp_lt_i32_e32 vcc, 21, v117
	v_cvt_pk_bf16_f32 v196, v196, v197
	s_nop 1
	v_cndmask_b32_e32 v197, 0, v112, vcc
	v_cmp_lt_i32_e32 vcc, 22, v117
	s_nop 1
	v_cndmask_b32_e32 v117, 0, v113, vcc
	v_cvt_pk_bf16_f32 v197, v197, v117
